# barriers 6, 7, 8, 10: the XCD leader skips the L2 writeback (P5, P6, P7, P9 publish only with drained write-through stores; the never-taken plain epilogue variants of P6/P9 are write-through too)
# baseline (speedup 1.0000x reference)
.LBB0_841:
	s_andn2_saveexec_b64 s[6:7], s[6:7]
	s_cbranch_execz .LBB0_861
	s_mov_b64 s[6:7], exec
	s_nop 0
	s_nop 0
	s_waitcnt lgkmcnt(0)
	s_waitcnt vmcnt(0)
	v_mbcnt_lo_u32_b32 v1, s6, 0
	v_mbcnt_hi_u32_b32 v1, s7, v1
	v_cmp_eq_u32_e32 vcc, 0, v1
	s_and_saveexec_b64 s[8:9], vcc
	s_cbranch_execz .LBB0_844
	s_bcnt1_i32_b64 s3, s[6:7]
	v_mov_b32_e32 v2, 0x3000
	v_mov_b32_e32 v3, s3
	global_atomic_add v2, v2, v3, s[28:29] offset:1024 sc0

.LBB0_975:
	s_andn2_saveexec_b64 s[6:7], s[6:7]
	s_cbranch_execz .LBB0_995
	s_mov_b64 s[6:7], exec
	s_nop 0
	s_nop 0
	s_waitcnt lgkmcnt(0)
	s_waitcnt vmcnt(0)
	v_mbcnt_lo_u32_b32 v1, s6, 0
	v_mbcnt_hi_u32_b32 v1, s7, v1
	v_cmp_eq_u32_e32 vcc, 0, v1
	s_and_saveexec_b64 s[10:11], vcc
	s_cbranch_execz .LBB0_978
	s_bcnt1_i32_b64 s3, s[6:7]
	v_mov_b32_e32 v2, 0x3000
	v_mov_b32_e32 v3, s3
	global_atomic_add v2, v2, v3, s[28:29] offset:1024 sc0

.LBB0_1298:
	s_andn2_saveexec_b64 s[4:5], s[4:5]
	s_cbranch_execz .LBB0_1318
	s_mov_b64 s[4:5], exec
	s_nop 0
	s_nop 0
	s_waitcnt lgkmcnt(0)
	s_waitcnt vmcnt(0)
	v_mbcnt_lo_u32_b32 v1, s4, 0
	v_mbcnt_hi_u32_b32 v1, s5, v1
	v_cmp_eq_u32_e32 vcc, 0, v1
	s_and_saveexec_b64 s[6:7], vcc
	s_cbranch_execz .LBB0_1301
	s_bcnt1_i32_b64 s4, s[4:5]
	v_mov_b32_e32 v2, 0x3000
	v_mov_b32_e32 v3, s4
	global_atomic_add v2, v2, v3, s[28:29] offset:1024 sc0
